# v12 + P4 full-tile epilogue: x residual loads in a 6-deep rolling window instead of one load pair per step
# baseline (speedup 1.0000x reference)
; __device__ __forceinline__ unsigned cvt_pk_bf16(float lo, float hi) { unsigned r; asm volatile("v_cvt_pk_bf16_f32 %0, %1, %2" : "=v"(r) : "v"(lo), "v"(hi)); return r; }
;     __device__ __forceinline__ void operator()(const f32x4 (&acc)[2][2][4][2], const Unit& u, int wr, int wc, int fr, int fq) const {
;     ...
;         if (u.kp < 0) {
;             const float* gp = gate + (size_t)(u.pm >> 3) * NMOD + col0;
;             f32x4 gg[2][2];
; #pragma unroll
;             for (int bj = 0; bj < 2; ++bj)
; #pragma unroll
;                 for (int n = 0; n < 2; ++n) gg[bj][n] = (*(const f32x4*)(gp + bj * HALF + 4 * n) + *(const f32x4*)(gp + MODSB_DELTA + bj * HALF + 4 * n)) * coef;
; #pragma unroll
;             for (int ai = 0; ai < 2; ++ai)
; #pragma unroll
;                 for (int m = 0; m < 4; ++m) {
;                     const int row = row0 + ai * HALF + m * 16;
;                     bf16_t* xp = X + (size_t)row * DM + col0;
; #pragma unroll
;                     for (int bj = 0; bj < 2; ++bj) {
;                         f32x4 b0, b1;
;                         if (BASE16) { const u32x4 bv = *(const u32x4*)(xp + bj * HALF);
;                             b0 = (f32x4){__builtin_bit_cast(float, bv.x << 16), __builtin_bit_cast(float, bv.x & 0xffff0000u), __builtin_bit_cast(float, bv.y << 16), __builtin_bit_cast(float, bv.y & 0xffff0000u)};
;                             b1 = (f32x4){__builtin_bit_cast(float, bv.z << 16), __builtin_bit_cast(float, bv.z & 0xffff0000u), __builtin_bit_cast(float, bv.w << 16), __builtin_bit_cast(float, bv.w & 0xffff0000u)}; }
;                         else { const float* bp = base32 + (size_t)row * DM + col0 + bj * HALF; b0 = __builtin_nontemporal_load((const f32x4*)bp); b1 = __builtin_nontemporal_load((const f32x4*)(bp + 4)); }
;                         const f32x4 o0 = b0 + gg[bj][0] * acc[ai][bj][m][0], o1 = b1 + gg[bj][1] * acc[ai][bj][m][1];
;                         u32x4 w; w.x = cvt_pk_bf16(o0[0], o0[1]); w.y = cvt_pk_bf16(o0[2], o0[3]); w.z = cvt_pk_bf16(o1[0], o1[1]); w.w = cvt_pk_bf16(o1[2], o1[3]);
;                         *(u32x4*)(xp + bj * HALF) = w;
;                     }
;                     if (m & 1) asm volatile("" ::: "memory");
.LBB0_509:
	s_ashr_i32 s24, s75, 3
	s_mul_hi_i32 s25, s24, 0x12000
	s_mul_i32 s24, s24, 0x12000
	s_add_u32 s24, s10, s24
	s_addc_u32 s25, s11, s25
	s_add_u32 s98, s24, s16
	s_addc_u32 s99, s25, s17
	v_lshlrev_b32_e32 v3, 2, v10
	global_load_dwordx4 v[12:15], v3, s[24:25]
	global_load_dwordx4 v[16:19], v3, s[24:25] offset:16
	global_load_dwordx4 v[20:23], v3, s[24:25] offset:512
	global_load_dwordx4 v[24:27], v3, s[24:25] offset:528
	global_load_dwordx4 v[28:31], v3, s[98:99]
	global_load_dwordx4 v[174:177], v3, s[98:99] offset:16
	global_load_dwordx4 v[178:181], v3, s[98:99] offset:512
	global_load_dwordx4 v[194:197], v3, s[98:99] offset:528
	v_lshlrev_b32_e32 v5, 12, v2
	v_lshlrev_b32_e32 v7, 13, v2
	v_lshl_add_u32 v5, v10, 1, v5
	v_add_u32_e32 v7, v7, v3
	global_load_dwordx4 v[198:201], v7, s[36:37] nt
	global_load_dwordx4 v[202:205], v7, s[36:37] offset:16 nt
	global_load_dwordx4 v[206:209], v7, s[36:37] offset:512 nt
	global_load_dwordx4 v[210:213], v7, s[36:37] offset:528 nt
	s_add_u32 s24, s36, 0x20000
	s_addc_u32 s25, s37, 0
	global_load_dwordx4 v[214:217], v7, s[24:25] nt
	global_load_dwordx4 v[218:221], v7, s[24:25] offset:16 nt
	s_add_u32 s24, s36, 0x20000
	s_addc_u32 s25, s37, 0
	global_load_dwordx4 v[222:225], v7, s[24:25] offset:512 nt
	global_load_dwordx4 v[226:229], v7, s[24:25] offset:528 nt
	s_add_u32 s24, s36, 0x40000
	s_addc_u32 s25, s37, 0
	global_load_dwordx4 v[230:233], v7, s[24:25] nt
	global_load_dwordx4 v[234:237], v7, s[24:25] offset:16 nt
	s_add_u32 s24, s36, 0x40000
	s_addc_u32 s25, s37, 0
	global_load_dwordx4 v[238:241], v7, s[24:25] offset:512 nt
	global_load_dwordx4 v[242:245], v7, s[24:25] offset:528 nt
	s_waitcnt vmcnt(12)
	v_pk_add_f32 v[12:13], v[12:13], v[28:29]
	v_pk_add_f32 v[14:15], v[14:15], v[30:31]
	v_pk_add_f32 v[16:17], v[16:17], v[174:175]
	v_pk_add_f32 v[18:19], v[18:19], v[176:177]
	v_pk_add_f32 v[20:21], v[20:21], v[178:179]
	v_pk_add_f32 v[22:23], v[22:23], v[180:181]
	v_pk_add_f32 v[24:25], v[24:25], v[194:195]
	v_pk_add_f32 v[26:27], v[26:27], v[196:197]
	v_pk_mul_f32 v[12:13], v[12:13], 0.5 op_sel_hi:[1,0]
	v_pk_mul_f32 v[14:15], v[14:15], 0.5 op_sel_hi:[1,0]
	v_pk_mul_f32 v[16:17], v[16:17], 0.5 op_sel_hi:[1,0]
	v_pk_mul_f32 v[18:19], v[18:19], 0.5 op_sel_hi:[1,0]
	v_pk_mul_f32 v[20:21], v[20:21], 0.5 op_sel_hi:[1,0]
	v_pk_mul_f32 v[22:23], v[22:23], 0.5 op_sel_hi:[1,0]
	v_pk_mul_f32 v[24:25], v[24:25], 0.5 op_sel_hi:[1,0]
	v_pk_mul_f32 v[26:27], v[26:27], 0.5 op_sel_hi:[1,0]
	s_waitcnt vmcnt(10)
	v_pk_fma_f32 v[198:199], v[158:159], v[12:13], v[198:199]
	v_pk_fma_f32 v[200:201], v[160:161], v[14:15], v[200:201]
	v_pk_fma_f32 v[202:203], v[154:155], v[16:17], v[202:203]
	v_pk_fma_f32 v[204:205], v[156:157], v[18:19], v[204:205]
	v_cvt_pk_bf16_f32 v198, v198, v199
	v_cvt_pk_bf16_f32 v199, v200, v201
	v_cvt_pk_bf16_f32 v200, v202, v203
	v_cvt_pk_bf16_f32 v201, v204, v205
	global_store_dwordx4 v5, v[198:201], s[8:9]
	s_add_u32 s24, s36, 0x60000
	s_addc_u32 s25, s37, 0
	global_load_dwordx4 v[202:205], v7, s[24:25] nt
	global_load_dwordx4 v[28:31], v7, s[24:25] offset:16 nt
	s_waitcnt vmcnt(11)
	v_pk_fma_f32 v[206:207], v[150:151], v[20:21], v[206:207]
	v_pk_fma_f32 v[208:209], v[152:153], v[22:23], v[208:209]
	v_pk_fma_f32 v[210:211], v[146:147], v[24:25], v[210:211]
	v_pk_fma_f32 v[212:213], v[148:149], v[26:27], v[212:213]
	v_cvt_pk_bf16_f32 v206, v206, v207
	v_cvt_pk_bf16_f32 v207, v208, v209
	v_cvt_pk_bf16_f32 v208, v210, v211
	v_cvt_pk_bf16_f32 v209, v212, v213
	global_store_dwordx4 v5, v[206:209], s[8:9] offset:256
	s_add_u32 s24, s36, 0x60000
	s_addc_u32 s25, s37, 0
	global_load_dwordx4 v[210:213], v7, s[24:25] offset:512 nt
	global_load_dwordx4 v[198:201], v7, s[24:25] offset:528 nt
	s_waitcnt vmcnt(12)
	v_pk_fma_f32 v[214:215], v[142:143], v[12:13], v[214:215]
	v_pk_fma_f32 v[216:217], v[144:145], v[14:15], v[216:217]
	v_pk_fma_f32 v[218:219], v[138:139], v[16:17], v[218:219]
	v_pk_fma_f32 v[220:221], v[140:141], v[18:19], v[220:221]
	v_cvt_pk_bf16_f32 v214, v214, v215
	v_cvt_pk_bf16_f32 v215, v216, v217
	v_cvt_pk_bf16_f32 v216, v218, v219
	v_cvt_pk_bf16_f32 v217, v220, v221
	s_add_u32 s98, s8, 0x10000
	s_addc_u32 s99, s9, 0
	global_store_dwordx4 v5, v[214:217], s[98:99]
	s_add_u32 s24, s36, 0x100000
	s_addc_u32 s25, s37, 0
	global_load_dwordx4 v[218:221], v7, s[24:25] nt
	global_load_dwordx4 v[206:209], v7, s[24:25] offset:16 nt
	s_waitcnt vmcnt(13)
	v_pk_fma_f32 v[222:223], v[134:135], v[20:21], v[222:223]
	v_pk_fma_f32 v[224:225], v[136:137], v[22:23], v[224:225]
	v_pk_fma_f32 v[226:227], v[130:131], v[24:25], v[226:227]
	v_pk_fma_f32 v[228:229], v[132:133], v[26:27], v[228:229]
	v_cvt_pk_bf16_f32 v222, v222, v223
	v_cvt_pk_bf16_f32 v223, v224, v225
	v_cvt_pk_bf16_f32 v224, v226, v227
	v_cvt_pk_bf16_f32 v225, v228, v229
	s_add_u32 s98, s8, 0x10000
	s_addc_u32 s99, s9, 0
	global_store_dwordx4 v5, v[222:225], s[98:99] offset:256
	s_add_u32 s24, s36, 0x100000
	s_addc_u32 s25, s37, 0
	global_load_dwordx4 v[226:229], v7, s[24:25] offset:512 nt
	global_load_dwordx4 v[214:217], v7, s[24:25] offset:528 nt
	s_waitcnt vmcnt(14)
	v_pk_fma_f32 v[230:231], v[126:127], v[12:13], v[230:231]
	v_pk_fma_f32 v[232:233], v[128:129], v[14:15], v[232:233]
	v_pk_fma_f32 v[234:235], v[122:123], v[16:17], v[234:235]
	v_pk_fma_f32 v[236:237], v[124:125], v[18:19], v[236:237]
	v_cvt_pk_bf16_f32 v230, v230, v231
	v_cvt_pk_bf16_f32 v231, v232, v233
	v_cvt_pk_bf16_f32 v232, v234, v235
	v_cvt_pk_bf16_f32 v233, v236, v237
	s_add_u32 s98, s8, 0x20000
	s_addc_u32 s99, s9, 0
	global_store_dwordx4 v5, v[230:233], s[98:99]
	s_add_u32 s24, s36, 0x120000
	s_addc_u32 s25, s37, 0
	global_load_dwordx4 v[234:237], v7, s[24:25] nt
	global_load_dwordx4 v[222:225], v7, s[24:25] offset:16 nt
	s_waitcnt vmcnt(15)
; __device__ __forceinline__ unsigned cvt_pk_bf16(float lo, float hi) { unsigned r; asm volatile("v_cvt_pk_bf16_f32 %0, %1, %2" : "=v"(r) : "v"(lo), "v"(hi)); return r; }
;     __device__ __forceinline__ void operator()(const f32x4 (&acc)[2][2][4][2], const Unit& u, int wr, int wc, int fr, int fq) const {
;     ...
;             for (int ai = 0; ai < 2; ++ai)
; #pragma unroll
;                 for (int m = 0; m < 4; ++m) {
;                     const int row = row0 + ai * HALF + m * 16;
;                     bf16_t* xp = X + (size_t)row * DM + col0;
; #pragma unroll
;                     for (int bj = 0; bj < 2; ++bj) {
;                         f32x4 b0, b1;
;                         if (BASE16) { const u32x4 bv = *(const u32x4*)(xp + bj * HALF);
;                             b0 = (f32x4){__builtin_bit_cast(float, bv.x << 16), __builtin_bit_cast(float, bv.x & 0xffff0000u), __builtin_bit_cast(float, bv.y << 16), __builtin_bit_cast(float, bv.y & 0xffff0000u)};
;                             b1 = (f32x4){__builtin_bit_cast(float, bv.z << 16), __builtin_bit_cast(float, bv.z & 0xffff0000u), __builtin_bit_cast(float, bv.w << 16), __builtin_bit_cast(float, bv.w & 0xffff0000u)}; }
;                         else { const float* bp = base32 + (size_t)row * DM + col0 + bj * HALF; b0 = __builtin_nontemporal_load((const f32x4*)bp); b1 = __builtin_nontemporal_load((const f32x4*)(bp + 4)); }
;                         const f32x4 o0 = b0 + gg[bj][0] * acc[ai][bj][m][0], o1 = b1 + gg[bj][1] * acc[ai][bj][m][1];
;                         u32x4 w; w.x = cvt_pk_bf16(o0[0], o0[1]); w.y = cvt_pk_bf16(o0[2], o0[3]); w.z = cvt_pk_bf16(o1[0], o1[1]); w.w = cvt_pk_bf16(o1[2], o1[3]);
;                         *(u32x4*)(xp + bj * HALF) = w;
;                     }
;                     if (m & 1) asm volatile("" ::: "memory");
	v_pk_fma_f32 v[238:239], v[118:119], v[20:21], v[238:239]
	v_pk_fma_f32 v[240:241], v[120:121], v[22:23], v[240:241]
	v_pk_fma_f32 v[242:243], v[114:115], v[24:25], v[242:243]
	v_pk_fma_f32 v[244:245], v[116:117], v[26:27], v[244:245]
	v_cvt_pk_bf16_f32 v238, v238, v239
	v_cvt_pk_bf16_f32 v239, v240, v241
	v_cvt_pk_bf16_f32 v240, v242, v243
	v_cvt_pk_bf16_f32 v241, v244, v245
	s_add_u32 s98, s8, 0x20000
	s_addc_u32 s99, s9, 0
	global_store_dwordx4 v5, v[238:241], s[98:99] offset:256
	s_add_u32 s24, s36, 0x120000
	s_addc_u32 s25, s37, 0
	global_load_dwordx4 v[242:245], v7, s[24:25] offset:512 nt
	global_load_dwordx4 v[230:233], v7, s[24:25] offset:528 nt
	s_waitcnt vmcnt(15)
	v_pk_fma_f32 v[202:203], v[110:111], v[12:13], v[202:203]
	v_pk_fma_f32 v[204:205], v[112:113], v[14:15], v[204:205]
	v_pk_fma_f32 v[28:29], v[106:107], v[16:17], v[28:29]
	v_pk_fma_f32 v[30:31], v[108:109], v[18:19], v[30:31]
	v_cvt_pk_bf16_f32 v202, v202, v203
	v_cvt_pk_bf16_f32 v203, v204, v205
	v_cvt_pk_bf16_f32 v204, v28, v29
	v_cvt_pk_bf16_f32 v205, v30, v31
	s_add_u32 s98, s8, 0x30000
	s_addc_u32 s99, s9, 0
	global_store_dwordx4 v5, v[202:205], s[98:99]
	s_add_u32 s24, s36, 0x140000
	s_addc_u32 s25, s37, 0
	global_load_dwordx4 v[28:31], v7, s[24:25] nt
	global_load_dwordx4 v[238:241], v7, s[24:25] offset:16 nt
	s_waitcnt vmcnt(15)
	v_pk_fma_f32 v[210:211], v[102:103], v[20:21], v[210:211]
	v_pk_fma_f32 v[212:213], v[104:105], v[22:23], v[212:213]
	v_pk_fma_f32 v[198:199], v[98:99], v[24:25], v[198:199]
	v_pk_fma_f32 v[200:201], v[100:101], v[26:27], v[200:201]
	v_cvt_pk_bf16_f32 v210, v210, v211
	v_cvt_pk_bf16_f32 v211, v212, v213
	v_cvt_pk_bf16_f32 v212, v198, v199
	v_cvt_pk_bf16_f32 v213, v200, v201
	s_add_u32 s98, s8, 0x30000
	s_addc_u32 s99, s9, 0
	global_store_dwordx4 v5, v[210:213], s[98:99] offset:256
	s_add_u32 s24, s36, 0x140000
	s_addc_u32 s25, s37, 0
	global_load_dwordx4 v[198:201], v7, s[24:25] offset:512 nt
	global_load_dwordx4 v[202:205], v7, s[24:25] offset:528 nt
	s_waitcnt vmcnt(15)
	v_pk_fma_f32 v[218:219], v[94:95], v[12:13], v[218:219]
	v_pk_fma_f32 v[220:221], v[96:97], v[14:15], v[220:221]
	v_pk_fma_f32 v[206:207], v[90:91], v[16:17], v[206:207]
	v_pk_fma_f32 v[208:209], v[92:93], v[18:19], v[208:209]
	v_cvt_pk_bf16_f32 v218, v218, v219
	v_cvt_pk_bf16_f32 v219, v220, v221
	v_cvt_pk_bf16_f32 v220, v206, v207
	v_cvt_pk_bf16_f32 v221, v208, v209
	s_add_u32 s98, s8, 0x80000
	s_addc_u32 s99, s9, 0
	global_store_dwordx4 v5, v[218:221], s[98:99]
	s_add_u32 s24, s36, 0x160000
	s_addc_u32 s25, s37, 0
	global_load_dwordx4 v[206:209], v7, s[24:25] nt
	global_load_dwordx4 v[210:213], v7, s[24:25] offset:16 nt
	s_waitcnt vmcnt(15)
	v_pk_fma_f32 v[226:227], v[86:87], v[20:21], v[226:227]
	v_pk_fma_f32 v[228:229], v[88:89], v[22:23], v[228:229]
	v_pk_fma_f32 v[214:215], v[82:83], v[24:25], v[214:215]
	v_pk_fma_f32 v[216:217], v[84:85], v[26:27], v[216:217]
	v_cvt_pk_bf16_f32 v226, v226, v227
	v_cvt_pk_bf16_f32 v227, v228, v229
	v_cvt_pk_bf16_f32 v228, v214, v215
	v_cvt_pk_bf16_f32 v229, v216, v217
	s_add_u32 s98, s8, 0x80000
	s_addc_u32 s99, s9, 0
	global_store_dwordx4 v5, v[226:229], s[98:99] offset:256
	s_add_u32 s24, s36, 0x160000
	s_addc_u32 s25, s37, 0
	global_load_dwordx4 v[214:217], v7, s[24:25] offset:512 nt
	global_load_dwordx4 v[218:221], v7, s[24:25] offset:528 nt
	s_waitcnt vmcnt(15)
	v_pk_fma_f32 v[234:235], v[78:79], v[12:13], v[234:235]
	v_pk_fma_f32 v[236:237], v[80:81], v[14:15], v[236:237]
	v_pk_fma_f32 v[222:223], v[74:75], v[16:17], v[222:223]
	v_pk_fma_f32 v[224:225], v[76:77], v[18:19], v[224:225]
	v_cvt_pk_bf16_f32 v234, v234, v235
	v_cvt_pk_bf16_f32 v235, v236, v237
	v_cvt_pk_bf16_f32 v236, v222, v223
	v_cvt_pk_bf16_f32 v237, v224, v225
	s_add_u32 s98, s8, 0x90000
	s_addc_u32 s99, s9, 0
	global_store_dwordx4 v5, v[234:237], s[98:99]
	s_waitcnt vmcnt(13)
	v_pk_fma_f32 v[242:243], v[70:71], v[20:21], v[242:243]
	v_pk_fma_f32 v[244:245], v[72:73], v[22:23], v[244:245]
	v_pk_fma_f32 v[230:231], v[66:67], v[24:25], v[230:231]
	v_pk_fma_f32 v[232:233], v[68:69], v[26:27], v[232:233]
	v_cvt_pk_bf16_f32 v242, v242, v243
	v_cvt_pk_bf16_f32 v243, v244, v245
	v_cvt_pk_bf16_f32 v244, v230, v231
	v_cvt_pk_bf16_f32 v245, v232, v233
	s_add_u32 s98, s8, 0x90000
	s_addc_u32 s99, s9, 0
	global_store_dwordx4 v5, v[242:245], s[98:99] offset:256
	s_waitcnt vmcnt(11)
	v_pk_fma_f32 v[28:29], v[62:63], v[12:13], v[28:29]
	v_pk_fma_f32 v[30:31], v[64:65], v[14:15], v[30:31]
	v_pk_fma_f32 v[238:239], v[58:59], v[16:17], v[238:239]
	v_pk_fma_f32 v[240:241], v[60:61], v[18:19], v[240:241]
	v_cvt_pk_bf16_f32 v28, v28, v29
	v_cvt_pk_bf16_f32 v29, v30, v31
	v_cvt_pk_bf16_f32 v30, v238, v239
	v_cvt_pk_bf16_f32 v31, v240, v241
	s_add_u32 s98, s8, 0xa0000
	s_addc_u32 s99, s9, 0
	global_store_dwordx4 v5, v[28:31], s[98:99]
	s_waitcnt vmcnt(9)
	v_pk_fma_f32 v[198:199], v[54:55], v[20:21], v[198:199]
	v_pk_fma_f32 v[200:201], v[56:57], v[22:23], v[200:201]
	v_pk_fma_f32 v[202:203], v[50:51], v[24:25], v[202:203]
	v_pk_fma_f32 v[204:205], v[52:53], v[26:27], v[204:205]
	v_cvt_pk_bf16_f32 v198, v198, v199
	v_cvt_pk_bf16_f32 v199, v200, v201
	v_cvt_pk_bf16_f32 v200, v202, v203
	v_cvt_pk_bf16_f32 v201, v204, v205
	s_add_u32 s98, s8, 0xa0000
	s_addc_u32 s99, s9, 0
	global_store_dwordx4 v5, v[198:201], s[98:99] offset:256
	s_waitcnt vmcnt(7)
	v_pk_fma_f32 v[206:207], v[46:47], v[12:13], v[206:207]
	v_pk_fma_f32 v[208:209], v[48:49], v[14:15], v[208:209]
	v_pk_fma_f32 v[210:211], v[42:43], v[16:17], v[210:211]
	v_pk_fma_f32 v[212:213], v[44:45], v[18:19], v[212:213]
	v_cvt_pk_bf16_f32 v206, v206, v207
	v_cvt_pk_bf16_f32 v207, v208, v209
	v_cvt_pk_bf16_f32 v208, v210, v211
	v_cvt_pk_bf16_f32 v209, v212, v213
	s_add_u32 s98, s8, 0xb0000
	s_addc_u32 s99, s9, 0
	global_store_dwordx4 v5, v[206:209], s[98:99]
	s_waitcnt vmcnt(5)
	v_pk_fma_f32 v[214:215], v[38:39], v[20:21], v[214:215]
	v_pk_fma_f32 v[216:217], v[40:41], v[22:23], v[216:217]
	v_pk_fma_f32 v[218:219], v[34:35], v[24:25], v[218:219]
	v_pk_fma_f32 v[220:221], v[36:37], v[26:27], v[220:221]
	v_cvt_pk_bf16_f32 v214, v214, v215
	v_cvt_pk_bf16_f32 v215, v216, v217
	v_cvt_pk_bf16_f32 v216, v218, v219
	v_cvt_pk_bf16_f32 v217, v220, v221
	s_add_u32 s98, s8, 0xb0000
	s_addc_u32 s99, s9, 0
	global_store_dwordx4 v5, v[214:217], s[98:99] offset:256
	s_and_b64 vcc, exec, s[2:3]
	s_mov_b64 s[2:3], -1
	s_cbranch_vccnz .LBB0_492
